# attention tile loop VALU trim: K/V LDS-DMA in SGPR-base + 32-bit offset form, K read addresses from 4 adds, V staged in natural key order so the 8 per-tile P permlane swaps are gone
# speedup vs baseline: 1.0145x; 1.0012x over previous
; __device__ __forceinline__ int v_rd_base(int lane) { return ((lane & 3) << 3) | (((lane >> 2) & 3) << 6) | (((lane >> 4) & 1) << 5) | (((lane >> 5) & 1) << 8); }
; #define WAIT_BAR(N) asm volatile("s_waitcnt vmcnt(" #N ") lgkmcnt(0)\n\ts_barrier" ::: "memory")
; template <bool FIXED> __device__ __forceinline__ void attn_unit(int b, int h, int qb, const bf16* __restrict__ P, bf16* __restrict__ MIX, const float* __restrict__ BT, const float* __restrict__ subg, ...
;     ...
;   float m_reg = -1e30f, l_reg = 0.f; f32x16 o[4] = {}; bf16x8 qr[4];
;   const bf16* Qw = P + (rowbase + qw0 + r32) * PW + h * 128 + m * 64 + hi * 8;
; #pragma unroll
;   for (int d0 = 0; d0 < 4; ++d0) qr[d0] = *reinterpret_cast<const bf16x8*>(Qw + d0 * 16);
;   const bf16* Kh = P + rowbase * PW + 1024 + h * 128; const bf16* Vh = P + rowbase * PW + 2048 + h * 128;
;   unsigned ksrc[2], vsrc[2];
; #pragma unroll
;   for (int i = 0; i < 2; ++i) { const int pk = wid * 2 + i;
;     { const int row = 4 * pk + (lane >> 4), cc = lane & 15; ksrc[i] = (unsigned)(row * PW + ((cc ^ (row & 7)) * 8)); }
;     { const int ob = pk * 1024 + lane * 16, sub = ob >> 9, kk = (sub >> 2) * 8 + ((ob & 511) >> 6), k = (kk & ~0xC) | ((kk & 4) << 1) | ((kk & 8) >> 1), c = (sub & 3) * 32 + ((ob & 63) >> 1);
;       vsrc[i] = (unsigned)(k * PW + c); } }
;   typedef __attribute__((address_space(3))) unsigned lds_u32;
;   typedef __attribute__((address_space(3))) unsigned char lds_u8;
;   lds_u8* const ring = (lds_u8*)lds + wid * 2048;
;     ...
;   const lds_cptr vp0 = (lds_cptr)lds + SHM_K + v_rd_base(lane);
;     ...
;   f32x16 p0, p1; float al, ca; bf16x8 pa0, pa1, pa2, pa3; const int NT = 2 * qb + 2;
;     ...
;   const int NTT = ATT_REP * NT;
;   DMA_TILE(0, 0); DMA_TILE(1, 1);
;   WAIT_BAR(4);
;   int slot = 0;
.LBB0_310:
	s_or_b64 exec, exec, s[0:1]
	s_ashr_i32 s1, s25, 6
	s_ashr_i32 s26, s25, 8
	s_and_b32 s24, s1, 3
	s_mul_i32 s6, s26, 0x180
	s_lshl_b32 s0, s24, 5
	s_ashr_i32 s7, s6, 31
	s_or_b32 s29, s0, s34
	s_lshl_b64 s[6:7], s[6:7], 2
	s_add_u32 s6, s10, s6
	s_addc_u32 s7, s11, s7
	global_load_dword v1, v145, s[6:7] offset:1020
	v_and_b32_e32 v134, 31, v0
	s_or_b32 s22, s54, s29
	v_bfe_u32 v167, v0, 5, 1
	v_lshlrev_b32_e32 v144, 4, v167
	s_lshl_b32 s8, s1, 3
	v_bfe_u32 v13, v0, 2, 2
	v_and_b32_e32 v168, 63, v0
	v_lshlrev_b32_e32 v166, 3, v168
	v_bfe_u32 v12, v0, 4, 2
	v_and_b32_e32 v15, 32, v0
	v_and_b32_e32 v16, 24, v166
	v_lshlrev_b32_e32 v19, 4, v0
	v_mov_b32_e32 v9, v145
	v_mov_b32_e32 v5, v145
	v_mov_b32_e32 v7, v145
	s_add_i32 s0, s34, s0
	s_lshl_b32 s38, s73, 9
	v_mov_b32_e32 v176, 0
	s_mov_b32 s23, s55
	s_lshl_b32 s28, s73, 1
	s_addk_i32 s29, 0xff51
	v_lshlrev_b32_e32 v171, 8, v134
	s_addk_i32 s38, 0x200
	s_mov_b32 s39, 0
	s_mov_b32 s44, 0
	s_mov_b32 s45, 0
	s_mov_b32 s56, 0
	v_mov_b32_e32 v22, v176
	v_mov_b32_e32 v23, v176
	v_mov_b32_e32 v24, v176
	v_mov_b32_e32 v25, v176
	v_mov_b32_e32 v26, v176
	v_mov_b32_e32 v27, v176
	v_mov_b32_e32 v28, v176
	v_mov_b32_e32 v29, v176
	v_mov_b32_e32 v30, v176
	v_mov_b32_e32 v31, v176
	v_mov_b32_e32 v32, 0
	v_mov_b32_e32 v33, v176
	v_mov_b32_e32 v34, v176
	v_mov_b32_e32 v35, v176
	v_mov_b32_e32 v36, v176
	v_mov_b32_e32 v37, v176
	v_mov_b32_e32 v38, v176
	v_mov_b32_e32 v39, v176
	v_mov_b32_e32 v40, v176
	v_mov_b32_e32 v41, v176
	v_mov_b32_e32 v42, v176
	v_mov_b32_e32 v43, v176
	v_mov_b32_e32 v44, v176
	v_mov_b32_e32 v45, v176
	v_mov_b32_e32 v46, v176
	v_mov_b32_e32 v47, v176
	v_mov_b32_e32 v48, 0
	v_mov_b32_e32 v49, v176
	v_mov_b32_e32 v50, v176
	v_mov_b32_e32 v51, v176
	v_mov_b32_e32 v52, v176
	v_mov_b32_e32 v53, v176
	v_mov_b32_e32 v54, v176
	v_mov_b32_e32 v55, v176
	v_mov_b32_e32 v56, v176
	v_mov_b32_e32 v57, v176
	v_mov_b32_e32 v58, v176
	v_mov_b32_e32 v59, v176
	v_mov_b32_e32 v60, v176
	v_mov_b32_e32 v61, v176
	v_mov_b32_e32 v62, v176
	v_mov_b32_e32 v63, v176
	s_waitcnt vmcnt(0)
	v_sub_f32_e32 v64, v1, v2
	v_or_b32_e32 v1, s22, v134
	v_mov_b64_e32 v[2:3], s[16:17]
	v_mad_u64_u32 v[2:3], s[6:7], v1, s70, v[2:3]
	s_lshl_b32 s6, s26, 6
	v_mad_i32_i24 v3, s55, v196, v3
	s_ashr_i32 s7, s6, 31
	v_lshl_add_u64 v[2:3], s[6:7], 1, v[2:3]
	v_lshl_add_u64 v[2:3], v[2:3], 0, v[144:145]
	global_load_dwordx4 v[112:115], v[2:3], off
	global_load_dwordx4 v[116:119], v[2:3], off offset:32
	global_load_dwordx4 v[120:123], v[2:3], off offset:64
	global_load_dwordx4 v[124:127], v[2:3], off offset:96
	v_lshrrev_b32_e32 v2, 2, v0
	s_and_b32 s6, s8, -16
	v_and_b32_e32 v14, 4, v2
	s_lshl_b32 s7, s1, 3
	s_and_b32 s7, s7, 8
	v_or3_b32 v2, v14, v13, s6
	v_or_b32_e32 v2, s7, v2
	v_mul_lo_u32 v2, v2, s35
	v_or3_b32 v4, v2, v15, v16
	v_or_b32_e32 v2, s8, v12
	v_bitop3_b32 v3, v12, v0, 15 bitop3:0x78
	v_and_b32_e32 v1, 15, v0
	v_mul_lo_u32 v2, v2, s35
	v_lshlrev_b32_e32 v17, 3, v3
	v_or_b32_e32 v8, v2, v17
	v_or_b32_e32 v2, 4, v12
	v_bitop3_b32 v1, v12, v1, 4 bitop3:0x36
	v_or_b32_e32 v2, s8, v2
	v_lshlrev_b32_e32 v18, 3, v1
	v_and_b32_e32 v1, 0xc0, v19
	v_lshlrev_b32_e32 v0, 1, v0
	v_mul_lo_u32 v2, v2, s35
	s_lshl_b32 s8, s1, 11
	v_and_b32_e32 v20, 32, v0
	v_add3_u32 v21, 0, v16, v1
	v_lshlrev_b64 v[0:1], 1, v[8:9]
	v_or_b32_e32 v6, v2, v18
	s_add_i32 s27, s8, 0
	v_lshl_add_u64 v[8:9], s[18:19], 0, v[0:1]
	v_or_b32_e32 v2, 64, v4
	s_add_i32 s8, s27, 0x4000
	v_lshl_add_u64 v[8:9], v[8:9], 0, s[36:37]
	s_mov_b32 m0, s27
	v_lshlrev_b64 v[4:5], 1, v[4:5]
	v_lshlrev_b64 v[6:7], 1, v[6:7]
	global_load_lds_dwordx4 v[8:9], off
	v_lshl_add_u64 v[8:9], s[20:21], 0, v[4:5]
	s_mov_b32 m0, s8
	v_lshl_add_u64 v[10:11], s[18:19], 0, v[6:7]
	global_load_lds_dwordx4 v[8:9], off
	v_lshl_add_u64 v[10:11], v[10:11], 0, s[36:37]
	s_add_i32 m0, s27, 0x400
	v_lshl_add_u64 v[8:9], v[8:9], 0, s[94:95]
	global_load_lds_dwordx4 v[10:11], off
	s_add_i32 m0, s27, 0x4400
	s_add_i32 s8, s27, 0xc000
	global_load_lds_dwordx4 v[8:9], off
	s_add_i32 m0, s27, 0x8000
	v_lshl_add_u64 v[0:1], s[88:89], 0, v[0:1]
	global_load_lds_dwordx4 v[0:1], off
	v_lshl_add_u64 v[0:1], s[90:91], 0, v[4:5]
	s_mov_b32 m0, s8
	v_mov_b32_e32 v3, v145
	global_load_lds_dwordx4 v[0:1], off
	v_lshl_add_u64 v[0:1], s[88:89], 0, v[6:7]
	s_add_i32 m0, s27, 0x8400
	s_lshl_b32 s8, s26, 7
	global_load_lds_dwordx4 v[0:1], off
	v_lshl_add_u64 v[0:1], v[2:3], 1, s[90:91]
	s_add_i32 m0, s27, 0xc400
	s_mul_i32 s1, s1, 0xc000
	global_load_lds_dwordx4 v[0:1], off
	v_or_b32_e32 v0, s8, v144
	v_and_b32_e32 v1, 0x70, v19
	v_bitop3_b32 v173, v0, v1, 32 bitop3:0x36
	v_bitop3_b32 v174, v0, v1, 64 bitop3:0x36
	v_bitop3_b32 v175, v0, v1, s64 bitop3:0x36
	v_or_b32_e32 v0, s6, v14
	v_or3_b32 v0, v0, s7, v13
	v_mul_lo_u32 v0, v0, s35
	v_bitop3_b32 v172, s8, v1, v144 bitop3:0x36
	v_add_u32_e32 v172, v172, v171
	v_add_u32_e32 v173, v173, v171
	v_add_u32_e32 v174, v174, v171
	v_add_u32_e32 v175, v175, v171
	v_or3_b32 v0, v0, v15, v16
	v_mov_b32_e32 v1, v145
	s_add_i32 s6, s1, 0x6000
	v_lshlrev_b64 v[136:137], 1, v[0:1]
	v_mov_b32_e32 v0, s6
	v_mad_u32_u24 v0, v12, s35, v0
	v_or_b32_e32 v0, v0, v18
	v_lshlrev_b32_e32 v138, 1, v0
	v_mov_b32_e32 v0, s1
	v_mad_u32_u24 v0, v12, s35, v0
	v_or_b32_e32 v0, v0, v17
	s_waitcnt vmcnt(4) lgkmcnt(0)
	s_barrier
	v_lshlrev_b32_e32 v2, 2, v167
	v_lshlrev_b32_e32 v140, 1, v0
	s_mul_i32 s1, s26, 0x600
	v_add_u32_e32 v0, s0, v134
	v_and_b32_e32 v8, 0x100, v166
	v_sub_u32_e32 v0, v0, v2
	s_add_i32 s0, s1, 0
	v_mov_b32_e32 v65, v64
	v_mov_b32_e32 v66, v64
	v_mov_b32_e32 v67, v64
	v_mov_b32_e32 v68, v64
	v_mov_b32_e32 v69, v64
	v_mov_b32_e32 v70, v64
	v_mov_b32_e32 v71, v64
	v_mov_b32_e32 v72, v64
	v_mov_b32_e32 v73, v64
	v_mov_b32_e32 v74, v64
	v_mov_b32_e32 v75, v64
	v_mov_b32_e32 v76, v64
	v_mov_b32_e32 v77, v64
	v_mov_b32_e32 v78, v64
	v_mov_b32_e32 v79, v64
	v_add3_u32 v170, v21, v20, v8
	v_lshl_add_u32 v178, v0, 2, s0
	s_mov_b64 s[0:1], s[92:93]
	v_mov_b32_e32 v0, 0
	v_mov_b32_e32 v1, v176
	v_mov_b32_e32 v2, v176
	v_mov_b32_e32 v3, v176
	v_mov_b32_e32 v4, v176
	v_mov_b32_e32 v5, v176
	v_mov_b32_e32 v6, v176
	v_mov_b32_e32 v7, v176
	v_mov_b32_e32 v8, v176
	v_mov_b32_e32 v9, v176
	v_mov_b32_e32 v10, v176
	v_mov_b32_e32 v11, v176
	v_mov_b32_e32 v12, v176
	v_mov_b32_e32 v13, v176
	v_mov_b32_e32 v14, v176
	v_mov_b32_e32 v15, v176
	v_mov_b32_e32 v16, 0
	v_mov_b32_e32 v17, v176
	v_mov_b32_e32 v18, v176
	v_mov_b32_e32 v19, v176
	v_mov_b32_e32 v20, v176
	v_mov_b32_e32 v21, v176
	s_waitcnt vmcnt(0)
	s_branch .LBB0_312

; #define SBAR() __builtin_amdgcn_sched_barrier(0)
; __device__ __forceinline__ int v_rd_base(int lane) { return ((lane & 3) << 3) | (((lane >> 2) & 3) << 6) | (((lane >> 4) & 1) << 5) | (((lane >> 5) & 1) << 8); }
; __device__ __forceinline__ void qkt(f32x16& p0, f32x16& p1, const char* Ks, const bf16x8* qr, int r32, int hi, int m, const f32x16& cinit) {
;   bf16x8 kf[8];
; #pragma unroll
;   for (int d0 = 0; d0 < 4; ++d0) { const int cb = (m * 64 + d0 * 16 + hi * 8) * 2;
;     kf[2 * d0] = *reinterpret_cast<const bf16x8*>(Ks + KSWZ(r32, cb)); kf[2 * d0 + 1] = *reinterpret_cast<const bf16x8*>(Ks + KSWZ(32 + r32, cb)); }
;   SBAR();
;   p0 = __builtin_amdgcn_mfma_f32_32x32x16_bf16(kf[0], qr[0], cinit, 0, 0, 0);
;   p1 = __builtin_amdgcn_mfma_f32_32x32x16_bf16(kf[1], qr[0], cinit, 0, 0, 0);
; #pragma unroll
;   for (int d0 = 1; d0 < 4; ++d0) {
;     p0 = __builtin_amdgcn_mfma_f32_32x32x16_bf16(kf[2 * d0], qr[d0], p0, 0, 0, 0);
;     p1 = __builtin_amdgcn_mfma_f32_32x32x16_bf16(kf[2 * d0 + 1], qr[d0], p1, 0, 0, 0); }
;   SBAR();
; }
; __device__ __forceinline__ void bias_mask(f32x16& p0, f32x16& p1, const float* bt, int base) {
; #pragma unroll
;   for (int r = 0; r < 16; ++r) { const int c = (r & 3) + 8 * (r >> 2); p0[r] += bt[base - c]; }
;   SBAR();
; #pragma unroll
;   for (int r = 0; r < 16; ++r) { const int c = (r & 3) + 8 * (r >> 2); p1[r] += bt[base - c - 32]; }
; }
; template <bool FIXED> __device__ __forceinline__ void attn_unit(int b, int h, int qb, const bf16* __restrict__ P, bf16* __restrict__ MIX, const float* __restrict__ BT, const float* __restrict__ subg, ...
;     ...
;   const lds_cptr vp0 = (lds_cptr)lds + SHM_K + v_rd_base(lane);
.LBB0_314:
	s_andn2_b64 vcc, exec, s[8:9]
	s_cbranch_vccnz .LBB0_316
	s_lshl_b32 s59, s45, 15
	s_add_i32 s8, s59, 0xffff8000
	s_cmp_gt_i32 s45, 0
	s_cselect_b32 s8, s8, 0x10000
	s_add_i32 s8, s27, s8
	s_add_u32 s98, s0, 0x1a380800
	s_addc_u32 s99, s1, 0
	s_mov_b32 m0, s8
	s_add_u32 s100, s0, s4
	s_addc_u32 s101, s1, s5
	global_load_lds_dwordx4 v140, s[98:99]
	s_add_i32 m0, s8, 0x4000
	s_nop 0
	global_load_lds_dwordx4 v136, s[100:101]
	s_add_i32 m0, s8, 0x400
	s_add_u32 s100, s0, s74
	s_addc_u32 s101, s1, s75
	global_load_lds_dwordx4 v138, s[98:99]
	s_add_i32 m0, s8, 0x4400
	s_nop 0
	global_load_lds_dwordx4 v136, s[100:101]
.LBB0_316:
	s_cmp_ge_i32 s39, s29
	s_mov_b64 s[8:9], -1
	s_cbranch_scc0 .LBB0_318
	v_add_u32_e32 v85, s59, v172
	v_add_u32_e32 v87, s59, v173
	v_add_u32_e32 v89, s59, v174
	v_add_u32_e32 v91, s59, v175
	ds_read_b128 v[80:83], v85
	ds_read_b128 v[96:99], v85 offset:8192
	ds_read_b128 v[198:201], v87
	ds_read_b128 v[202:205], v87 offset:8192
	ds_read_b128 v[206:209], v89
	ds_read_b128 v[210:213], v89 offset:8192
	ds_read_b128 v[214:217], v91
	ds_read_b128 v[218:221], v91 offset:8192
	v_add_u32_e32 v230, s44, v178
	v_add_u32_e32 v230, 0x18914, v230
	s_waitcnt lgkmcnt(0)
	v_mfma_f32_32x32x16_bf16 v[80:95], v[80:83], v[112:115], 0
	v_mfma_f32_32x32x16_bf16 v[96:111], v[96:99], v[112:115], 0
	v_mfma_f32_32x32x16_bf16 v[80:95], v[198:201], v[116:119], v[80:95]
	v_mfma_f32_32x32x16_bf16 v[96:111], v[202:205], v[116:119], v[96:111]
	v_mfma_f32_32x32x16_bf16 v[80:95], v[206:209], v[120:123], v[80:95]
	v_mfma_f32_32x32x16_bf16 v[96:111], v[210:213], v[120:123], v[96:111]
	v_mfma_f32_32x32x16_bf16 v[80:95], v[214:217], v[124:127], v[80:95]
	v_mfma_f32_32x32x16_bf16 v[96:111], v[218:221], v[124:127], v[96:111]
	ds_read2_b32 v[198:199], v230 offset0:58 offset1:59
	ds_read2_b32 v[200:201], v230 offset0:56 offset1:57
	ds_read2_b32 v[202:203], v230 offset0:50 offset1:51
	ds_read2_b32 v[204:205], v230 offset0:48 offset1:49
	ds_read2_b32 v[206:207], v230 offset0:42 offset1:43
	ds_read2_b32 v[208:209], v230 offset0:40 offset1:41
	ds_read2_b32 v[210:211], v230 offset0:34 offset1:35
	ds_read2_b32 v[212:213], v230 offset0:32 offset1:33
	ds_read2_b32 v[214:215], v230 offset0:26 offset1:27
	ds_read2_b32 v[216:217], v230 offset0:24 offset1:25
	ds_read2_b32 v[218:219], v230 offset0:18 offset1:19
	ds_read2_b32 v[220:221], v230 offset0:16 offset1:17
	ds_read2_b32 v[222:223], v230 offset0:10 offset1:11
	ds_read2_b32 v[224:225], v230 offset0:8 offset1:9
	ds_read2_b32 v[226:227], v230 offset0:2 offset1:3
	ds_read2_b32 v[228:229], v230 offset0:0 offset1:1
	s_mov_b64 s[8:9], 0
	s_waitcnt lgkmcnt(0)
	v_add_f32_e32 v80, v80, v199
	v_add_f32_e32 v81, v81, v198
	v_pk_add_f32 v[82:83], v[82:83], v[200:201] op_sel:[0,1] op_sel_hi:[1,0]
	v_pk_add_f32 v[84:85], v[84:85], v[202:203] op_sel:[0,1] op_sel_hi:[1,0]
	v_pk_add_f32 v[86:87], v[86:87], v[204:205] op_sel:[0,1] op_sel_hi:[1,0]
	v_pk_add_f32 v[88:89], v[88:89], v[206:207] op_sel:[0,1] op_sel_hi:[1,0]
	v_pk_add_f32 v[90:91], v[90:91], v[208:209] op_sel:[0,1] op_sel_hi:[1,0]
	v_pk_add_f32 v[92:93], v[92:93], v[210:211] op_sel:[0,1] op_sel_hi:[1,0]
	v_pk_add_f32 v[94:95], v[94:95], v[212:213] op_sel:[0,1] op_sel_hi:[1,0]
	v_pk_add_f32 v[96:97], v[96:97], v[214:215] op_sel:[0,1] op_sel_hi:[1,0]
	v_pk_add_f32 v[98:99], v[98:99], v[216:217] op_sel:[0,1] op_sel_hi:[1,0]
	v_pk_add_f32 v[100:101], v[100:101], v[218:219] op_sel:[0,1] op_sel_hi:[1,0]
	v_pk_add_f32 v[102:103], v[102:103], v[220:221] op_sel:[0,1] op_sel_hi:[1,0]
	v_pk_add_f32 v[104:105], v[104:105], v[222:223] op_sel:[0,1] op_sel_hi:[1,0]
	v_pk_add_f32 v[106:107], v[106:107], v[224:225] op_sel:[0,1] op_sel_hi:[1,0]
	v_pk_add_f32 v[108:109], v[108:109], v[226:227] op_sel:[0,1] op_sel_hi:[1,0]
	v_pk_add_f32 v[110:111], v[110:111], v[228:229] op_sel:[0,1] op_sel_hi:[1,0]
.LBB0_318:
	s_andn2_b64 vcc, exec, s[8:9]
	s_cbranch_vccnz .LBB0_320
	v_add_u32_e32 v80, s59, v172
	v_add_u32_e32 v81, s59, v173
	v_add_u32_e32 v82, s59, v174
	v_add_u32_e32 v83, s59, v175
	ds_read_b128 v[96:99], v80
	ds_read_b128 v[198:201], v80 offset:8192
	ds_read_b128 v[202:205], v81
	ds_read_b128 v[206:209], v81 offset:8192
	ds_read_b128 v[210:213], v82
	ds_read_b128 v[214:217], v82 offset:8192
	ds_read_b128 v[218:221], v83
	ds_read_b128 v[222:225], v83 offset:8192
	s_waitcnt lgkmcnt(0)
	v_mfma_f32_32x32x16_bf16 v[80:95], v[96:99], v[112:115], v[64:79]
	v_mfma_f32_32x32x16_bf16 v[96:111], v[198:201], v[112:115], v[64:79]
	v_mfma_f32_32x32x16_bf16 v[80:95], v[202:205], v[116:119], v[80:95]
	v_mfma_f32_32x32x16_bf16 v[96:111], v[206:209], v[116:119], v[96:111]
	v_mfma_f32_32x32x16_bf16 v[80:95], v[210:213], v[120:123], v[80:95]
	v_mfma_f32_32x32x16_bf16 v[96:111], v[214:217], v[120:123], v[96:111]
	v_mfma_f32_32x32x16_bf16 v[80:95], v[218:221], v[124:127], v[80:95]
	v_mfma_f32_32x32x16_bf16 v[96:111], v[222:225], v[124:127], v[96:111]
; #define SBAR() __builtin_amdgcn_sched_barrier(0)
; __device__ __forceinline__ void finishSM(f32x16& p0, f32x16& p1, float alpha, float& l_reg, bf16x8& pa0, bf16x8& pa1, bf16x8& pa2, bf16x8& pa3) {
; #pragma unroll
;   for (int r = 0; r < 16; ++r) p1[r] = __builtin_amdgcn_exp2f(p1[r]);
;   float ps = 0;
; #pragma unroll
;   for (int r = 0; r < 16; ++r) ps += p0[r];
; #pragma unroll
;   for (int r = 0; r < 16; ++r) ps += p1[r];
;   { auto rr = __builtin_amdgcn_permlane32_swap(__float_as_uint(ps), __float_as_uint(ps), false, false);
;     ps = __uint_as_float(rr[0]) + __uint_as_float(rr[1]); }
;   l_reg = l_reg * alpha + ps;
;     ...
;   PK4(p0, 0, pa0); PK4(p0, 8, pa1); PK4(p1, 0, pa2); PK4(p1, 8, pa3);
;     ...
; }
; __device__ __forceinline__ void pv_all(f32x16* o, lds_cptr vp, bf16x8 pa0, bf16x8 pa1, bf16x8 pa2, bf16x8 pa3) {
;   VFrag fa, fb;
;   v_read<0>(fa, vp); v_read<1>(fb, vp); SBAR();
;   pv_slice(o, fa, pa0); SBAR(); v_read<2>(fa, vp); SBAR();
;   pv_slice(o, fb, pa1); SBAR(); v_read<3>(fb, vp); SBAR();
;   pv_slice(o, fa, pa2); SBAR();
;   pv_slice(o, fb, pa3); SBAR();
; }
.LBB0_320:
	v_add_u32_e32 v244, s59, v170
	ds_read_b64_tr_b16 v[232:233], v244 offset:16384
	ds_read_b64_tr_b16 v[236:237], v244 offset:16896
	ds_read_b64_tr_b16 v[240:241], v244 offset:17408
	ds_read_b64_tr_b16 v[198:199], v244 offset:17920
	ds_read_b64_tr_b16 v[234:235], v244 offset:18432
	ds_read_b64_tr_b16 v[238:239], v244 offset:18944
	ds_read_b64_tr_b16 v[242:243], v244 offset:19456
	ds_read_b64_tr_b16 v[200:201], v244 offset:19968
	ds_read_b64_tr_b16 v[202:203], v244 offset:20480
	ds_read_b64_tr_b16 v[206:207], v244 offset:20992
	ds_read_b64_tr_b16 v[210:211], v244 offset:21504
	ds_read_b64_tr_b16 v[214:215], v244 offset:22016
	ds_read_b64_tr_b16 v[204:205], v244 offset:22528
	ds_read_b64_tr_b16 v[208:209], v244 offset:23040
	ds_read_b64_tr_b16 v[212:213], v244 offset:23552
	ds_read_b64_tr_b16 v[216:217], v244 offset:24064
	s_nop 1
	v_exp_f32_e32 v179, v80
	v_exp_f32_e32 v180, v81
	v_exp_f32_e32 v181, v82
	v_exp_f32_e32 v83, v83
	v_add_f32_e32 v80, 0, v179
	v_exp_f32_e32 v84, v84
	v_add_f32_e32 v80, v180, v80
	v_exp_f32_e32 v85, v85
	v_add_f32_e32 v80, v181, v80
	v_exp_f32_e32 v86, v86
	v_add_f32_e32 v80, v83, v80
	v_exp_f32_e32 v87, v87
	v_add_f32_e32 v80, v84, v80
	v_add_f32_e32 v80, v85, v80
	v_add_f32_e32 v80, v86, v80
	v_add_f32_e32 v80, v87, v80
	v_cvt_pk_bf16_f32 v82, v179, v180
	v_cvt_pk_bf16_f32 v83, v181, v83
	v_cvt_pk_bf16_f32 v84, v84, v85
	v_cvt_pk_bf16_f32 v85, v86, v87
	ds_read_b64_tr_b16 v[246:247], v244 offset:24576
	ds_read_b64_tr_b16 v[218:219], v244 offset:25088
	ds_read_b64_tr_b16 v[222:223], v244 offset:25600
	ds_read_b64_tr_b16 v[250:251], v244 offset:26112
	ds_read_b64_tr_b16 v[248:249], v244 offset:26624
	ds_read_b64_tr_b16 v[220:221], v244 offset:27136
	ds_read_b64_tr_b16 v[224:225], v244 offset:27648
	ds_read_b64_tr_b16 v[252:253], v244 offset:28160
	s_waitcnt lgkmcnt(8)
	v_exp_f32_e32 v88, v88
	v_mfma_f32_32x32x16_bf16 v[0:15], v[82:85], v[232:235], v[0:15]
	v_exp_f32_e32 v89, v89
	v_exp_f32_e32 v90, v90
	v_add_f32_e32 v80, v88, v80
	v_exp_f32_e32 v91, v91
	v_add_f32_e32 v80, v89, v80
	v_mfma_f32_32x32x16_bf16 v[16:31], v[82:85], v[236:239], v[16:31]
	v_exp_f32_e32 v92, v92
	v_add_f32_e32 v80, v90, v80
	v_exp_f32_e32 v93, v93
	v_add_f32_e32 v80, v91, v80
	v_exp_f32_e32 v94, v94
	v_add_f32_e32 v80, v92, v80
	v_mfma_f32_32x32x16_bf16 v[32:47], v[82:85], v[240:243], v[32:47]
	v_exp_f32_e32 v95, v95
	v_add_f32_e32 v80, v93, v80
	v_add_f32_e32 v80, v94, v80
	v_add_f32_e32 v80, v95, v80
	v_cvt_pk_bf16_f32 v86, v88, v89
	v_cvt_pk_bf16_f32 v87, v90, v91
	v_mfma_f32_32x32x16_bf16 v[48:63], v[82:85], v[198:201], v[48:63]
	v_cvt_pk_bf16_f32 v88, v92, v93
	v_cvt_pk_bf16_f32 v89, v94, v95
	s_nop 0
	v_exp_f32_e32 v96, v96
	v_exp_f32_e32 v97, v97
	v_mfma_f32_32x32x16_bf16 v[0:15], v[86:89], v[202:205], v[0:15]
	v_exp_f32_e32 v98, v98
	v_add_f32_e32 v80, v96, v80
	v_exp_f32_e32 v99, v99
	v_add_f32_e32 v80, v97, v80
	v_exp_f32_e32 v100, v100
	v_add_f32_e32 v80, v98, v80
	v_mfma_f32_32x32x16_bf16 v[16:31], v[86:89], v[206:209], v[16:31]
	v_exp_f32_e32 v101, v101
	v_add_f32_e32 v80, v99, v80
	v_exp_f32_e32 v102, v102
	v_add_f32_e32 v80, v100, v80
	v_exp_f32_e32 v103, v103
	v_add_f32_e32 v80, v101, v80
	v_mfma_f32_32x32x16_bf16 v[32:47], v[86:89], v[210:213], v[32:47]
	v_add_f32_e32 v80, v102, v80
	v_add_f32_e32 v80, v103, v80
	v_cvt_pk_bf16_f32 v90, v96, v97
	v_cvt_pk_bf16_f32 v91, v98, v99
	v_cvt_pk_bf16_f32 v92, v100, v101
	v_mfma_f32_32x32x16_bf16 v[48:63], v[86:89], v[214:217], v[48:63]
	v_cvt_pk_bf16_f32 v93, v102, v103
	ds_read_b64_tr_b16 v[86:87], v244 offset:28672
	ds_read_b64_tr_b16 v[198:199], v244 offset:29184
	ds_read_b64_tr_b16 v[202:203], v244 offset:29696
	ds_read_b64_tr_b16 v[206:207], v244 offset:30208
	ds_read_b64_tr_b16 v[88:89], v244 offset:30720
	ds_read_b64_tr_b16 v[200:201], v244 offset:31232
	ds_read_b64_tr_b16 v[204:205], v244 offset:31744
	ds_read_b64_tr_b16 v[208:209], v244 offset:32256
	s_waitcnt lgkmcnt(8)
	v_exp_f32_e32 v104, v104
	v_exp_f32_e32 v105, v105
	v_mfma_f32_32x32x16_bf16 v[0:15], v[90:93], v[246:249], v[0:15]
	v_exp_f32_e32 v106, v106
	v_add_f32_e32 v80, v104, v80
	v_exp_f32_e32 v107, v107
	v_add_f32_e32 v80, v105, v80
	v_exp_f32_e32 v108, v108
	v_add_f32_e32 v80, v106, v80
	v_mfma_f32_32x32x16_bf16 v[16:31], v[90:93], v[218:221], v[16:31]
	v_exp_f32_e32 v109, v109
	v_add_f32_e32 v80, v107, v80
	v_exp_f32_e32 v110, v110
	v_add_f32_e32 v80, v108, v80
	v_exp_f32_e32 v111, v111
	v_add_f32_e32 v80, v109, v80
	v_mfma_f32_32x32x16_bf16 v[32:47], v[90:93], v[222:225], v[32:47]
	v_add_f32_e32 v80, v110, v80
	v_add_f32_e32 v80, v111, v80
	v_cvt_pk_bf16_f32 v94, v104, v105
	v_cvt_pk_bf16_f32 v95, v106, v107
	v_cvt_pk_bf16_f32 v96, v108, v109
	v_mfma_f32_32x32x16_bf16 v[48:63], v[90:93], v[250:253], v[48:63]
	v_cvt_pk_bf16_f32 v97, v110, v111
	v_mov_b32_e32 v81, v80
	s_nop 1
	s_waitcnt lgkmcnt(0)
	v_permlane32_swap_b32_e32 v80, v81
	v_mfma_f32_32x32x16_bf16 v[0:15], v[94:97], v[86:89], v[0:15]
	v_mfma_f32_32x32x16_bf16 v[16:31], v[94:97], v[198:201], v[16:31]
	v_mfma_f32_32x32x16_bf16 v[32:47], v[94:97], v[202:205], v[32:47]
	v_mfma_f32_32x32x16_bf16 v[48:63], v[94:97], v[206:209], v[48:63]
	s_mov_b64 s[8:9], -1
	s_and_b64 vcc, exec, s[6:7]
	s_cbranch_vccz .LBB0_322
	s_waitcnt vmcnt(0) lgkmcnt(0)
	s_barrier
	s_mov_b64 s[8:9], 0
